# grid barrier: blocks 0-7 (one per XCD) issue an extra un-waited buffer_wbl2 sc1 on non-leader arrival so the leader write-back finds the L2 mostly clean
# baseline (speedup 1.0000x reference)
; __device__ __forceinline__ unsigned xb_ld(unsigned* p)              { return __hip_atomic_load(p, __ATOMIC_RELAXED, __HIP_MEMORY_SCOPE_AGENT); }
; __device__ __forceinline__ unsigned xb_add(unsigned* p, unsigned v) { return __hip_atomic_fetch_add(p, v, __ATOMIC_RELAXED, __HIP_MEMORY_SCOPE_AGENT); }
; #define XB_SPIN(cond, bar) do { unsigned _sp = 0; while (cond) { __builtin_amdgcn_s_sleep(1); \
;     if ((++_sp & 255u) == 0u) { if (xb_ld(&(bar)[XB_TMO])) break; if (_sp > XB_SPIN_CAP) { atomicAdd(&(bar)[XB_TMO], 1u); break; } } } } while (0)
; __device__ __forceinline__ void xcd_barrier(const XcdBarrier& b) {
;     ...
;         const unsigned old = xb_add(&bar[XB_XSUB(b.x)], 1u);
;         const unsigned gen = old / nloc;
;         if (old + 1u == (gen + 1u) * nloc) {
;             __builtin_amdgcn_fence(__ATOMIC_RELEASE, "agent");
;             asm volatile("s_waitcnt vmcnt(0)" ::: "memory");
;             const unsigned og = xb_add(&bar[XB_TOP], 1u);
;             const unsigned tg = og / nx;
;             if (og + 1u == (tg + 1u) * nx) xb_add(&bar[XB_TOPGEN], 1u);
;             else XB_SPIN(xb_ld(&bar[XB_TOPGEN]) == tg, bar);
;             __builtin_amdgcn_fence(__ATOMIC_ACQUIRE, "agent");
;             xb_add(&bar[XB_XGEN(b.x)], 1u);
;             asm volatile("s_waitcnt vmcnt(0)" ::: "memory");
;         } else {
;             XB_SPIN(xb_ld(&bar[XB_XGEN(b.x)]) == gen, bar);
.LBB0_78:
	s_or_b64 exec, exec, s[12:13]
	v_cvt_f32_u32_e32 v4, v2
	s_waitcnt vmcnt(0)
	v_readfirstlane_b32 s3, v3
	v_sub_u32_e32 v3, 0, v2
	v_rcp_iflag_f32_e32 v4, v4
	v_add_u32_e32 v5, s3, v1
	v_mul_f32_e32 v4, 0x4f7ffffe, v4
	v_cvt_u32_f32_e32 v4, v4
	v_mul_lo_u32 v1, v3, v4
	v_mul_hi_u32 v1, v4, v1
	v_add_u32_e32 v1, v4, v1
	v_mul_hi_u32 v1, v5, v1
	v_mul_lo_u32 v3, v1, v2
	v_sub_u32_e32 v3, v5, v3
	v_add_u32_e32 v4, 1, v1
	v_cmp_ge_u32_e32 vcc, v3, v2
	s_nop 1
	v_cndmask_b32_e32 v1, v1, v4, vcc
	v_sub_u32_e32 v4, v3, v2
	v_cndmask_b32_e32 v3, v3, v4, vcc
	v_add_u32_e32 v4, 1, v1
	v_cmp_ge_u32_e32 vcc, v3, v2
	v_add_u32_e32 v3, 1, v5
	s_nop 0
	v_cndmask_b32_e32 v1, v1, v4, vcc
	v_mul_lo_u32 v4, v2, v1
	v_add_u32_e32 v2, v4, v2
	v_cmp_ne_u32_e32 vcc, v3, v2
	s_and_saveexec_b64 s[6:7], vcc
	s_xor_b64 s[10:11], exec, s[6:7]
	s_cbranch_execz .LBB0_92
	v_readlane_b32 vcc_lo, v246, 0
	s_cmp_lt_u32 vcc_lo, 8
	s_cbranch_scc0 .Lpfl_1
	buffer_wbl2 sc1
.Lpfl_1:
	buffer_inv sc1
	s_waitcnt lgkmcnt(0)
	v_mov_b32_e32 v0, 0x2000
	global_load_dword v0, v0, s[8:9] offset:1024 sc1
	s_add_u32 s16, s8, 0x2400
	s_addc_u32 s17, s9, 0
	s_waitcnt vmcnt(0)
	v_cmp_eq_u32_e32 vcc, v0, v1
	s_and_saveexec_b64 s[12:13], vcc
	s_cbranch_execz .LBB0_91
	s_add_u32 s14, s70, 0x50200
	s_addc_u32 s15, s71, 0
	s_mov_b32 s3, 1
	s_mov_b64 s[18:19], 0
	v_mov_b32_e32 v0, 0
	s_branch .LBB0_82

; __device__ __forceinline__ unsigned xb_ld(unsigned* p)              { return __hip_atomic_load(p, __ATOMIC_RELAXED, __HIP_MEMORY_SCOPE_AGENT); }
; __device__ __forceinline__ unsigned xb_add(unsigned* p, unsigned v) { return __hip_atomic_fetch_add(p, v, __ATOMIC_RELAXED, __HIP_MEMORY_SCOPE_AGENT); }
; #define XB_SPIN(cond, bar) do { unsigned _sp = 0; while (cond) { __builtin_amdgcn_s_sleep(1); \
;     if ((++_sp & 255u) == 0u) { if (xb_ld(&(bar)[XB_TMO])) break; if (_sp > XB_SPIN_CAP) { atomicAdd(&(bar)[XB_TMO], 1u); break; } } } } while (0)
; __device__ __forceinline__ void xcd_barrier(const XcdBarrier& b) {
;     ...
;         const unsigned old = xb_add(&bar[XB_XSUB(b.x)], 1u);
;         const unsigned gen = old / nloc;
;         if (old + 1u == (gen + 1u) * nloc) {
;             __builtin_amdgcn_fence(__ATOMIC_RELEASE, "agent");
;             asm volatile("s_waitcnt vmcnt(0)" ::: "memory");
;             const unsigned og = xb_add(&bar[XB_TOP], 1u);
;             const unsigned tg = og / nx;
;             if (og + 1u == (tg + 1u) * nx) xb_add(&bar[XB_TOPGEN], 1u);
;             else XB_SPIN(xb_ld(&bar[XB_TOPGEN]) == tg, bar);
;             __builtin_amdgcn_fence(__ATOMIC_ACQUIRE, "agent");
;             xb_add(&bar[XB_XGEN(b.x)], 1u);
;             asm volatile("s_waitcnt vmcnt(0)" ::: "memory");
;         } else {
;             XB_SPIN(xb_ld(&bar[XB_XGEN(b.x)]) == gen, bar);
.LBB0_164:
	s_or_b64 exec, exec, s[30:31]
	v_cvt_f32_u32_e32 v4, v2
	s_waitcnt vmcnt(0)
	v_readfirstlane_b32 s3, v3
	v_sub_u32_e32 v3, 0, v2
	v_rcp_iflag_f32_e32 v4, v4
	v_add_u32_e32 v5, s3, v1
	v_mul_f32_e32 v4, 0x4f7ffffe, v4
	v_cvt_u32_f32_e32 v4, v4
	v_mul_lo_u32 v1, v3, v4
	v_mul_hi_u32 v1, v4, v1
	v_add_u32_e32 v1, v4, v1
	v_mul_hi_u32 v1, v5, v1
	v_mul_lo_u32 v3, v1, v2
	v_sub_u32_e32 v3, v5, v3
	v_add_u32_e32 v4, 1, v1
	v_cmp_ge_u32_e32 vcc, v3, v2
	s_nop 1
	v_cndmask_b32_e32 v1, v1, v4, vcc
	v_sub_u32_e32 v4, v3, v2
	v_cndmask_b32_e32 v3, v3, v4, vcc
	v_add_u32_e32 v4, 1, v1
	v_cmp_ge_u32_e32 vcc, v3, v2
	v_add_u32_e32 v3, 1, v5
	s_nop 0
	v_cndmask_b32_e32 v1, v1, v4, vcc
	v_mul_lo_u32 v4, v2, v1
	v_add_u32_e32 v2, v4, v2
	v_cmp_ne_u32_e32 vcc, v3, v2
	s_and_saveexec_b64 s[6:7], vcc
	s_xor_b64 s[10:11], exec, s[6:7]
	s_cbranch_execz .LBB0_178
	v_readlane_b32 vcc_lo, v246, 0
	s_cmp_lt_u32 vcc_lo, 8
	s_cbranch_scc0 .Lpfl_2
	buffer_wbl2 sc1
.Lpfl_2:
	buffer_inv sc1
	s_waitcnt lgkmcnt(0)
	v_mov_b32_e32 v0, 0x2000
	global_load_dword v0, v0, s[8:9] offset:1024 sc1
	s_add_u32 s54, s8, 0x2400
	s_addc_u32 s55, s9, 0
	s_waitcnt vmcnt(0)
	v_cmp_eq_u32_e32 vcc, v0, v1
	s_and_saveexec_b64 s[30:31], vcc
	s_cbranch_execz .LBB0_177
	s_add_u32 s34, s70, 0x50200
	s_addc_u32 s35, s71, 0
	s_mov_b32 s3, 1
	s_mov_b64 s[58:59], 0
	v_mov_b32_e32 v0, 0
	s_branch .LBB0_168

; __device__ __forceinline__ unsigned xb_ld(unsigned* p)              { return __hip_atomic_load(p, __ATOMIC_RELAXED, __HIP_MEMORY_SCOPE_AGENT); }
; __device__ __forceinline__ unsigned xb_add(unsigned* p, unsigned v) { return __hip_atomic_fetch_add(p, v, __ATOMIC_RELAXED, __HIP_MEMORY_SCOPE_AGENT); }
; #define XB_SPIN(cond, bar) do { unsigned _sp = 0; while (cond) { __builtin_amdgcn_s_sleep(1); \
;     if ((++_sp & 255u) == 0u) { if (xb_ld(&(bar)[XB_TMO])) break; if (_sp > XB_SPIN_CAP) { atomicAdd(&(bar)[XB_TMO], 1u); break; } } } } while (0)
; __device__ __forceinline__ void xcd_barrier(const XcdBarrier& b) {
;     ...
;         const unsigned old = xb_add(&bar[XB_XSUB(b.x)], 1u);
;         const unsigned gen = old / nloc;
;         if (old + 1u == (gen + 1u) * nloc) {
;             __builtin_amdgcn_fence(__ATOMIC_RELEASE, "agent");
;             asm volatile("s_waitcnt vmcnt(0)" ::: "memory");
;             const unsigned og = xb_add(&bar[XB_TOP], 1u);
;             const unsigned tg = og / nx;
;             if (og + 1u == (tg + 1u) * nx) xb_add(&bar[XB_TOPGEN], 1u);
;             else XB_SPIN(xb_ld(&bar[XB_TOPGEN]) == tg, bar);
;             __builtin_amdgcn_fence(__ATOMIC_ACQUIRE, "agent");
;             xb_add(&bar[XB_XGEN(b.x)], 1u);
;             asm volatile("s_waitcnt vmcnt(0)" ::: "memory");
;         } else {
;             XB_SPIN(xb_ld(&bar[XB_XGEN(b.x)]) == gen, bar);
.LBB0_220:
	s_or_b64 exec, exec, s[10:11]
	v_cvt_f32_u32_e32 v4, v2
	s_waitcnt vmcnt(0)
	v_readfirstlane_b32 s3, v3
	v_sub_u32_e32 v3, 0, v2
	v_rcp_iflag_f32_e32 v4, v4
	v_add_u32_e32 v5, s3, v1
	v_mul_f32_e32 v4, 0x4f7ffffe, v4
	v_cvt_u32_f32_e32 v4, v4
	v_mul_lo_u32 v1, v3, v4
	v_mul_hi_u32 v1, v4, v1
	v_add_u32_e32 v1, v4, v1
	v_mul_hi_u32 v1, v5, v1
	v_mul_lo_u32 v3, v1, v2
	v_sub_u32_e32 v3, v5, v3
	v_add_u32_e32 v4, 1, v1
	v_cmp_ge_u32_e32 vcc, v3, v2
	s_nop 1
	v_cndmask_b32_e32 v1, v1, v4, vcc
	v_sub_u32_e32 v4, v3, v2
	v_cndmask_b32_e32 v3, v3, v4, vcc
	v_add_u32_e32 v4, 1, v1
	v_cmp_ge_u32_e32 vcc, v3, v2
	v_add_u32_e32 v3, 1, v5
	s_nop 0
	v_cndmask_b32_e32 v1, v1, v4, vcc
	v_mul_lo_u32 v4, v2, v1
	v_add_u32_e32 v2, v4, v2
	v_cmp_ne_u32_e32 vcc, v3, v2
	s_and_saveexec_b64 s[6:7], vcc
	s_xor_b64 s[8:9], exec, s[6:7]
	s_cbranch_execz .LBB0_234
	v_readlane_b32 vcc_lo, v246, 0
	s_cmp_lt_u32 vcc_lo, 8
	s_cbranch_scc0 .Lpfl_3
	buffer_wbl2 sc1
.Lpfl_3:
	buffer_inv sc1
	s_waitcnt lgkmcnt(0)
	v_mov_b32_e32 v0, 0x2000
	global_load_dword v0, v0, s[4:5] offset:1024 sc1
	s_add_u32 s34, s4, 0x2400
	s_addc_u32 s35, s5, 0
	s_waitcnt vmcnt(0)
	v_cmp_eq_u32_e32 vcc, v0, v1
	s_and_saveexec_b64 s[10:11], vcc
	s_cbranch_execz .LBB0_233
	s_add_u32 s30, s70, 0x50200
	s_addc_u32 s31, s71, 0
	s_mov_b32 s3, 1
	s_mov_b64 s[54:55], 0
	v_mov_b32_e32 v0, 0
	s_branch .LBB0_224

; __device__ __forceinline__ unsigned xb_ld(unsigned* p)              { return __hip_atomic_load(p, __ATOMIC_RELAXED, __HIP_MEMORY_SCOPE_AGENT); }
; __device__ __forceinline__ unsigned xb_add(unsigned* p, unsigned v) { return __hip_atomic_fetch_add(p, v, __ATOMIC_RELAXED, __HIP_MEMORY_SCOPE_AGENT); }
; #define XB_SPIN(cond, bar) do { unsigned _sp = 0; while (cond) { __builtin_amdgcn_s_sleep(1); \
;     if ((++_sp & 255u) == 0u) { if (xb_ld(&(bar)[XB_TMO])) break; if (_sp > XB_SPIN_CAP) { atomicAdd(&(bar)[XB_TMO], 1u); break; } } } } while (0)
; __device__ __forceinline__ void xcd_barrier(const XcdBarrier& b) {
;     ...
;         const unsigned old = xb_add(&bar[XB_XSUB(b.x)], 1u);
;         const unsigned gen = old / nloc;
;         if (old + 1u == (gen + 1u) * nloc) {
;             __builtin_amdgcn_fence(__ATOMIC_RELEASE, "agent");
;             asm volatile("s_waitcnt vmcnt(0)" ::: "memory");
;             const unsigned og = xb_add(&bar[XB_TOP], 1u);
;             const unsigned tg = og / nx;
;             if (og + 1u == (tg + 1u) * nx) xb_add(&bar[XB_TOPGEN], 1u);
;             else XB_SPIN(xb_ld(&bar[XB_TOPGEN]) == tg, bar);
;             __builtin_amdgcn_fence(__ATOMIC_ACQUIRE, "agent");
;             xb_add(&bar[XB_XGEN(b.x)], 1u);
;             asm volatile("s_waitcnt vmcnt(0)" ::: "memory");
;         } else {
;             XB_SPIN(xb_ld(&bar[XB_XGEN(b.x)]) == gen, bar);
.LBB0_756:
	s_or_b64 exec, exec, s[10:11]
	v_cvt_f32_u32_e32 v4, v2
	s_waitcnt vmcnt(0)
	v_readfirstlane_b32 s2, v3
	v_sub_u32_e32 v3, 0, v2
	v_rcp_iflag_f32_e32 v4, v4
	v_add_u32_e32 v5, s2, v1
	v_mul_f32_e32 v4, 0x4f7ffffe, v4
	v_cvt_u32_f32_e32 v4, v4
	v_mul_lo_u32 v1, v3, v4
	v_mul_hi_u32 v1, v4, v1
	v_add_u32_e32 v1, v4, v1
	v_mul_hi_u32 v1, v5, v1
	v_mul_lo_u32 v3, v1, v2
	v_sub_u32_e32 v3, v5, v3
	v_add_u32_e32 v4, 1, v1
	v_cmp_ge_u32_e32 vcc, v3, v2
	s_nop 1
	v_cndmask_b32_e32 v1, v1, v4, vcc
	v_sub_u32_e32 v4, v3, v2
	v_cndmask_b32_e32 v3, v3, v4, vcc
	v_add_u32_e32 v4, 1, v1
	v_cmp_ge_u32_e32 vcc, v3, v2
	v_add_u32_e32 v3, 1, v5
	s_nop 0
	v_cndmask_b32_e32 v1, v1, v4, vcc
	v_mul_lo_u32 v4, v2, v1
	v_add_u32_e32 v2, v4, v2
	v_cmp_ne_u32_e32 vcc, v3, v2
	s_and_saveexec_b64 s[6:7], vcc
	s_xor_b64 s[8:9], exec, s[6:7]
	s_cbranch_execz .LBB0_770
	v_readlane_b32 vcc_lo, v246, 0
	s_cmp_lt_u32 vcc_lo, 8
	s_cbranch_scc0 .Lpfl_7
	buffer_wbl2 sc1
.Lpfl_7:
	buffer_inv sc1
	s_waitcnt lgkmcnt(0)
	v_mov_b32_e32 v0, 0x2000
	global_load_dword v0, v0, s[4:5] offset:1024 sc1
	s_add_u32 s34, s4, 0x2400
	s_addc_u32 s35, s5, 0
	s_waitcnt vmcnt(0)
	v_cmp_eq_u32_e32 vcc, v0, v1
	s_and_saveexec_b64 s[10:11], vcc
	s_cbranch_execz .LBB0_769
	s_add_u32 s30, s70, 0x50200
	s_addc_u32 s31, s71, 0
	s_mov_b32 s3, 1
	s_mov_b64 s[52:53], 0
	v_mov_b32_e32 v0, 0
	s_branch .LBB0_760

; __device__ __forceinline__ unsigned xb_ld(unsigned* p)              { return __hip_atomic_load(p, __ATOMIC_RELAXED, __HIP_MEMORY_SCOPE_AGENT); }
; #define XB_SPIN(cond, bar) do { unsigned _sp = 0; while (cond) { __builtin_amdgcn_s_sleep(1); \
;     if ((++_sp & 255u) == 0u) { if (xb_ld(&(bar)[XB_TMO])) break; if (_sp > XB_SPIN_CAP) { atomicAdd(&(bar)[XB_TMO], 1u); break; } } } } while (0)
; __device__ __forceinline__ void xcd_barrier(const XcdBarrier& b) {
;     ...
;         } else {
;             XB_SPIN(xb_ld(&bar[XB_XGEN(b.x)]) == gen, bar);
;             __builtin_amdgcn_fence(__ATOMIC_ACQUIRE, "agent");
;             asm volatile("s_waitcnt vmcnt(0)" ::: "memory");
.Lpfl_11:
	buffer_inv sc1
	s_waitcnt lgkmcnt(0)
	v_mov_b32_e32 v0, 0x2000
	global_load_dword v0, v0, s[4:5] offset:1024 sc1
	s_add_u32 s34, s4, 0x2400
	s_addc_u32 s35, s5, 0
	s_waitcnt vmcnt(0)
	v_cmp_eq_u32_e32 vcc, v0, v1
	s_and_saveexec_b64 s[10:11], vcc
	s_cbranch_execz .LBB0_1101
	s_add_u32 s30, s70, 0x50200
	s_addc_u32 s31, s71, 0
	s_mov_b32 s3, 1
	s_mov_b64 s[42:43], 0
	v_mov_b32_e32 v0, 0
	s_branch .LBB0_1092

; __device__ __forceinline__ unsigned xb_ld(unsigned* p)              { return __hip_atomic_load(p, __ATOMIC_RELAXED, __HIP_MEMORY_SCOPE_AGENT); }
; __device__ __forceinline__ unsigned xb_add(unsigned* p, unsigned v) { return __hip_atomic_fetch_add(p, v, __ATOMIC_RELAXED, __HIP_MEMORY_SCOPE_AGENT); }
; #define XB_SPIN(cond, bar) do { unsigned _sp = 0; while (cond) { __builtin_amdgcn_s_sleep(1); \
;     if ((++_sp & 255u) == 0u) { if (xb_ld(&(bar)[XB_TMO])) break; if (_sp > XB_SPIN_CAP) { atomicAdd(&(bar)[XB_TMO], 1u); break; } } } } while (0)
; __device__ __forceinline__ void xcd_barrier(const XcdBarrier& b) {
;     ...
;         const unsigned old = xb_add(&bar[XB_XSUB(b.x)], 1u);
;         const unsigned gen = old / nloc;
;         if (old + 1u == (gen + 1u) * nloc) {
;             __builtin_amdgcn_fence(__ATOMIC_RELEASE, "agent");
;             asm volatile("s_waitcnt vmcnt(0)" ::: "memory");
;             const unsigned og = xb_add(&bar[XB_TOP], 1u);
;             const unsigned tg = og / nx;
;             if (og + 1u == (tg + 1u) * nx) xb_add(&bar[XB_TOPGEN], 1u);
;             else XB_SPIN(xb_ld(&bar[XB_TOPGEN]) == tg, bar);
;             __builtin_amdgcn_fence(__ATOMIC_ACQUIRE, "agent");
;             xb_add(&bar[XB_XGEN(b.x)], 1u);
;             asm volatile("s_waitcnt vmcnt(0)" ::: "memory");
;         } else {
;             XB_SPIN(xb_ld(&bar[XB_XGEN(b.x)]) == gen, bar);
.LBB0_1228:
	s_or_b64 exec, exec, s[30:31]
	v_cvt_f32_u32_e32 v4, v2
	s_waitcnt vmcnt(0)
	v_readfirstlane_b32 s2, v3
	v_sub_u32_e32 v3, 0, v2
	v_rcp_iflag_f32_e32 v4, v4
	v_add_u32_e32 v5, s2, v1
	v_mul_f32_e32 v4, 0x4f7ffffe, v4
	v_cvt_u32_f32_e32 v4, v4
	v_mul_lo_u32 v1, v3, v4
	v_mul_hi_u32 v1, v4, v1
	v_add_u32_e32 v1, v4, v1
	v_mul_hi_u32 v1, v5, v1
	v_mul_lo_u32 v3, v1, v2
	v_sub_u32_e32 v3, v5, v3
	v_add_u32_e32 v4, 1, v1
	v_cmp_ge_u32_e32 vcc, v3, v2
	s_nop 1
	v_cndmask_b32_e32 v1, v1, v4, vcc
	v_sub_u32_e32 v4, v3, v2
	v_cndmask_b32_e32 v3, v3, v4, vcc
	v_add_u32_e32 v4, 1, v1
	v_cmp_ge_u32_e32 vcc, v3, v2
	v_add_u32_e32 v3, 1, v5
	s_nop 0
	v_cndmask_b32_e32 v1, v1, v4, vcc
	v_mul_lo_u32 v4, v2, v1
	v_add_u32_e32 v2, v4, v2
	v_cmp_ne_u32_e32 vcc, v3, v2
	s_and_saveexec_b64 s[6:7], vcc
	s_xor_b64 s[10:11], exec, s[6:7]
	s_cbranch_execz .LBB0_1242
	v_readlane_b32 vcc_lo, v246, 0
	s_cmp_lt_u32 vcc_lo, 8
	s_cbranch_scc0 .Lpfl_13
	buffer_wbl2 sc1
.Lpfl_13:
	buffer_inv sc1
	s_waitcnt lgkmcnt(0)
	v_mov_b32_e32 v0, 0x2000
	global_load_dword v0, v0, s[8:9] offset:1024 sc1
	s_add_u32 s42, s8, 0x2400
	s_addc_u32 s43, s9, 0
	s_waitcnt vmcnt(0)
	v_cmp_eq_u32_e32 vcc, v0, v1
	s_and_saveexec_b64 s[30:31], vcc
	s_cbranch_execz .LBB0_1241
	s_add_u32 s34, s70, 0x50200
	s_addc_u32 s35, s71, 0
	s_mov_b32 s3, 1
	s_mov_b64 s[46:47], 0
	v_mov_b32_e32 v0, 0
	s_branch .LBB0_1232

; __device__ __forceinline__ unsigned xb_ld(unsigned* p)              { return __hip_atomic_load(p, __ATOMIC_RELAXED, __HIP_MEMORY_SCOPE_AGENT); }
; #define XB_SPIN(cond, bar) do { unsigned _sp = 0; while (cond) { __builtin_amdgcn_s_sleep(1); \
;     if ((++_sp & 255u) == 0u) { if (xb_ld(&(bar)[XB_TMO])) break; if (_sp > XB_SPIN_CAP) { atomicAdd(&(bar)[XB_TMO], 1u); break; } } } } while (0)
; __device__ __forceinline__ void xcd_barrier(const XcdBarrier& b) {
;     ...
;         } else {
;             XB_SPIN(xb_ld(&bar[XB_XGEN(b.x)]) == gen, bar);
;             __builtin_amdgcn_fence(__ATOMIC_ACQUIRE, "agent");
;             asm volatile("s_waitcnt vmcnt(0)" ::: "memory");
.Lpfl_15:
	buffer_inv sc1
	s_waitcnt lgkmcnt(0)
	v_mov_b32_e32 v0, 0x2000
	global_load_dword v0, v0, s[4:5] offset:1024 sc1
	s_add_u32 s14, s4, 0x2400
	s_addc_u32 s15, s5, 0
	s_waitcnt vmcnt(0)
	v_cmp_eq_u32_e32 vcc, v0, v1
	s_and_saveexec_b64 s[10:11], vcc
	s_cbranch_execz .LBB0_1442
	s_add_u32 s12, s70, 0x50200
	s_addc_u32 s13, s71, 0
	s_mov_b32 s3, 1
	s_mov_b64 s[30:31], 0
	v_mov_b32_e32 v0, 0
	s_branch .LBB0_1433

; __device__ __forceinline__ unsigned xb_ld(unsigned* p)              { return __hip_atomic_load(p, __ATOMIC_RELAXED, __HIP_MEMORY_SCOPE_AGENT); }
; #define XB_SPIN(cond, bar) do { unsigned _sp = 0; while (cond) { __builtin_amdgcn_s_sleep(1); \
;     if ((++_sp & 255u) == 0u) { if (xb_ld(&(bar)[XB_TMO])) break; if (_sp > XB_SPIN_CAP) { atomicAdd(&(bar)[XB_TMO], 1u); break; } } } } while (0)
; __device__ __forceinline__ void xcd_barrier(const XcdBarrier& b) {
;     ...
;         } else {
;             XB_SPIN(xb_ld(&bar[XB_XGEN(b.x)]) == gen, bar);
;             __builtin_amdgcn_fence(__ATOMIC_ACQUIRE, "agent");
;             asm volatile("s_waitcnt vmcnt(0)" ::: "memory");
.Lpfl_16:
	buffer_inv sc1
	s_waitcnt lgkmcnt(0)
	v_mov_b32_e32 v0, 0x2000
	global_load_dword v0, v0, s[4:5] offset:1024 sc1
	s_add_u32 s14, s4, 0x2400
	s_addc_u32 s15, s5, 0
	s_waitcnt vmcnt(0)
	v_cmp_eq_u32_e32 vcc, v0, v1
	s_and_saveexec_b64 s[10:11], vcc
	s_cbranch_execz .LBB0_1667
	s_add_u32 s12, s70, 0x50200
	s_addc_u32 s13, s71, 0
	s_mov_b32 s3, 1
	s_mov_b64 s[20:21], 0
	v_mov_b32_e32 v0, 0
	s_branch .LBB0_1658

; __device__ __forceinline__ unsigned xb_ld(unsigned* p)              { return __hip_atomic_load(p, __ATOMIC_RELAXED, __HIP_MEMORY_SCOPE_AGENT); }
; #define XB_SPIN(cond, bar) do { unsigned _sp = 0; while (cond) { __builtin_amdgcn_s_sleep(1); \
;     if ((++_sp & 255u) == 0u) { if (xb_ld(&(bar)[XB_TMO])) break; if (_sp > XB_SPIN_CAP) { atomicAdd(&(bar)[XB_TMO], 1u); break; } } } } while (0)
; __device__ __forceinline__ void xcd_barrier(const XcdBarrier& b) {
;     ...
;         } else {
;             XB_SPIN(xb_ld(&bar[XB_XGEN(b.x)]) == gen, bar);
;             __builtin_amdgcn_fence(__ATOMIC_ACQUIRE, "agent");
;             asm volatile("s_waitcnt vmcnt(0)" ::: "memory");
.Lpfl_17:
	buffer_inv sc1
	s_waitcnt lgkmcnt(0)
	v_mov_b32_e32 v0, 0x2000
	global_load_dword v0, v0, s[4:5] offset:1024 sc1
	s_add_u32 s14, s4, 0x2400
	s_addc_u32 s15, s5, 0
	s_waitcnt vmcnt(0)
	v_cmp_eq_u32_e32 vcc, v0, v1
	s_and_saveexec_b64 s[10:11], vcc
	s_cbranch_execz .LBB0_1725
	s_add_u32 s12, s70, 0x50200
	s_addc_u32 s13, s71, 0
	s_mov_b32 s3, 1
	s_mov_b64 s[16:17], 0
	v_mov_b32_e32 v0, 0
	s_branch .LBB0_1716

; __device__ __forceinline__ unsigned xb_ld(unsigned* p)              { return __hip_atomic_load(p, __ATOMIC_RELAXED, __HIP_MEMORY_SCOPE_AGENT); }
; __device__ __forceinline__ unsigned xb_add(unsigned* p, unsigned v) { return __hip_atomic_fetch_add(p, v, __ATOMIC_RELAXED, __HIP_MEMORY_SCOPE_AGENT); }
; #define XB_SPIN(cond, bar) do { unsigned _sp = 0; while (cond) { __builtin_amdgcn_s_sleep(1); \
;     if ((++_sp & 255u) == 0u) { if (xb_ld(&(bar)[XB_TMO])) break; if (_sp > XB_SPIN_CAP) { atomicAdd(&(bar)[XB_TMO], 1u); break; } } } } while (0)
; __device__ __forceinline__ void xcd_barrier(const XcdBarrier& b) {
;     ...
;         const unsigned old = xb_add(&bar[XB_XSUB(b.x)], 1u);
;         const unsigned gen = old / nloc;
;         if (old + 1u == (gen + 1u) * nloc) {
;             __builtin_amdgcn_fence(__ATOMIC_RELEASE, "agent");
;             asm volatile("s_waitcnt vmcnt(0)" ::: "memory");
;             const unsigned og = xb_add(&bar[XB_TOP], 1u);
;             const unsigned tg = og / nx;
;             if (og + 1u == (tg + 1u) * nx) xb_add(&bar[XB_TOPGEN], 1u);
;             else XB_SPIN(xb_ld(&bar[XB_TOPGEN]) == tg, bar);
;             __builtin_amdgcn_fence(__ATOMIC_ACQUIRE, "agent");
;             xb_add(&bar[XB_XGEN(b.x)], 1u);
;             asm volatile("s_waitcnt vmcnt(0)" ::: "memory");
;         } else {
;             XB_SPIN(xb_ld(&bar[XB_XGEN(b.x)]) == gen, bar);
.LBB0_2077:
	s_or_b64 exec, exec, s[6:7]
	v_cvt_f32_u32_e32 v4, v2
	s_waitcnt vmcnt(0)
	v_readfirstlane_b32 s4, v3
	v_sub_u32_e32 v3, 0, v2
	v_rcp_iflag_f32_e32 v4, v4
	v_add_u32_e32 v5, s4, v1
	v_mul_f32_e32 v4, 0x4f7ffffe, v4
	v_cvt_u32_f32_e32 v4, v4
	v_mul_lo_u32 v1, v3, v4
	v_mul_hi_u32 v1, v4, v1
	v_add_u32_e32 v1, v4, v1
	v_mul_hi_u32 v1, v5, v1
	v_mul_lo_u32 v3, v1, v2
	v_sub_u32_e32 v3, v5, v3
	v_add_u32_e32 v4, 1, v1
	v_cmp_ge_u32_e32 vcc, v3, v2
	s_nop 1
	v_cndmask_b32_e32 v1, v1, v4, vcc
	v_sub_u32_e32 v4, v3, v2
	v_cndmask_b32_e32 v3, v3, v4, vcc
	v_add_u32_e32 v4, 1, v1
	v_cmp_ge_u32_e32 vcc, v3, v2
	v_add_u32_e32 v3, 1, v5
	s_nop 0
	v_cndmask_b32_e32 v1, v1, v4, vcc
	v_mul_lo_u32 v4, v2, v1
	v_add_u32_e32 v2, v4, v2
	v_cmp_ne_u32_e32 vcc, v3, v2
	s_and_saveexec_b64 s[4:5], vcc
	s_xor_b64 s[4:5], exec, s[4:5]
	s_cbranch_execz .LBB0_2091
	v_readlane_b32 vcc_lo, v246, 0
	s_cmp_lt_u32 vcc_lo, 8
	s_cbranch_scc0 .Lpfl_22
	buffer_wbl2 sc1
.Lpfl_22:
	buffer_inv sc1
	s_waitcnt lgkmcnt(0)
	v_mov_b32_e32 v0, 0x2000
	global_load_dword v0, v0, s[2:3] offset:1024 sc1
	s_add_u32 s10, s2, 0x2400
	s_addc_u32 s11, s3, 0
	s_waitcnt vmcnt(0)
	v_cmp_eq_u32_e32 vcc, v0, v1
	s_and_saveexec_b64 s[6:7], vcc
	s_cbranch_execz .LBB0_2090
	s_add_u32 s8, s70, 0x50200
	s_addc_u32 s9, s71, 0
	s_mov_b32 s22, 1
	s_mov_b64 s[12:13], 0
	v_mov_b32_e32 v0, 0
	s_branch .LBB0_2081
